# grid barrier wait loops poll back to back (no s_sleep between polls)
# speedup vs baseline: 1.0019x; 1.0019x over previous
.LBB0_931:
	s_and_b32 s29, s8, 0xff
	s_mov_b64 s[38:39], -1
	s_cmp_lg_u32 s29, 0
	s_mov_b64 s[42:43], -1
	s_nop 0
	s_cbranch_scc1 .LBB0_934
	v_readlane_b32 s40, v245, 0
	v_readlane_b32 s41, v245, 1
	s_nop 4
	global_load_dword v2, v1, s[40:41] sc1
	s_waitcnt vmcnt(0)
	v_cmp_eq_u32_e32 vcc, 0, v2
	s_cbranch_vccnz .LBB0_936
	s_mov_b64 s[42:43], 0
	s_mov_b64 s[40:41], -1
